# band-prompt attention: all 8 K-fragment LDS reads of a tile issued up front (8 buffers) before the QK MFMAs
# speedup vs baseline: 1.0043x; 1.0043x over previous
.LBB0_554:
	s_waitcnt lgkmcnt(0)
	v_sub_f32_e32 v66, v2, v127
	v_add_u32_e32 v2, s39, v172
	v_add_u32_e32 v12, v2, v173
	v_add_u32_e32 v2, v2, v174
	ds_read_b128 v[4:7], v12
	ds_read_b128 v[8:11], v12 offset:32
	ds_read_b128 v[132:135], v12 offset:64
	ds_read_b128 v[140:143], v12 offset:96
	ds_read_b128 v[144:147], v2
	ds_read_b128 v[212:215], v2 offset:32
	ds_read_b128 v[216:219], v2 offset:64
	ds_read_b128 v[220:223], v2 offset:96
	v_mov_b32_e32 v67, v66
	v_mov_b32_e32 v68, v66
	v_mov_b32_e32 v69, v66
	v_mov_b32_e32 v70, v66
	v_mov_b32_e32 v71, v66
	v_mov_b32_e32 v72, v66
	v_mov_b32_e32 v73, v66
	v_mov_b32_e32 v74, v66
	v_mov_b32_e32 v75, v66
	v_mov_b32_e32 v76, v66
	v_mov_b32_e32 v77, v66
	v_mov_b32_e32 v78, v66
	v_mov_b32_e32 v79, v66
	v_mov_b32_e32 v80, v66
	v_mov_b32_e32 v81, v66
	s_andn2_b64 vcc, exec, s[24:25]
	s_waitcnt lgkmcnt(7)
	v_mfma_f32_32x32x16_bf16 v[82:97], v[4:7], v[102:105], v[66:81]
	s_waitcnt lgkmcnt(6)
	v_mfma_f32_32x32x16_bf16 v[82:97], v[8:11], v[106:109], v[82:97]
	s_waitcnt lgkmcnt(5)
	v_mfma_f32_32x32x16_bf16 v[82:97], v[132:135], v[110:113], v[82:97]
	s_waitcnt lgkmcnt(4)
	v_mfma_f32_32x32x16_bf16 v[82:97], v[140:143], v[114:117], v[82:97]
	s_waitcnt lgkmcnt(3)
	v_mfma_f32_32x32x16_bf16 v[66:81], v[144:147], v[102:105], v[66:81]
	s_waitcnt lgkmcnt(2)
	v_mfma_f32_32x32x16_bf16 v[66:81], v[212:215], v[106:109], v[66:81]
	s_waitcnt lgkmcnt(1)
	v_mfma_f32_32x32x16_bf16 v[66:81], v[216:219], v[110:113], v[66:81]
	s_waitcnt lgkmcnt(0)
	v_mfma_f32_32x32x16_bf16 v[66:81], v[220:223], v[114:117], v[66:81]
	s_cbranch_vccnz .LBB0_556
	v_add_u32_e32 v2, s38, v205
	v_add_u32_e32 v134, 29, v2
	v_med3_i32 v134, v134, s28, v207
	v_lshl_add_u32 v136, v134, 2, s26
	v_add_u32_e32 v134, 28, v2
	v_med3_i32 v134, v134, s28, v207
	v_lshl_add_u32 v137, v134, 2, s26
	v_add_u32_e32 v134, 23, v2
	v_med3_i32 v134, v134, s28, v207
	v_add_u32_e32 v142, 13, v2
	v_lshl_add_u32 v138, v134, 2, s26
	v_add_u32_e32 v134, 22, v2
	v_med3_i32 v142, v142, s28, v207
	v_add_u32_e32 v4, 63, v2
	v_add_u32_e32 v5, 62, v2
	v_add_u32_e32 v6, 61, v2
	v_add_u32_e32 v7, 60, v2
	v_add_u32_e32 v8, 55, v2
	v_add_u32_e32 v9, 54, v2
	v_add_u32_e32 v10, 53, v2
	v_add_u32_e32 v11, 52, v2
	v_add_u32_e32 v12, 47, v2
	v_add_u32_e32 v13, 46, v2
	v_add_u32_e32 v14, 45, v2
	v_add_u32_e32 v15, 44, v2
	v_add_u32_e32 v16, 39, v2
	v_add_u32_e32 v17, 38, v2
	v_add_u32_e32 v129, 37, v2
	v_med3_i32 v134, v134, s28, v207
	v_lshl_add_u32 v144, v142, 2, s26
	v_add_u32_e32 v142, 12, v2
	v_med3_i32 v4, v4, s28, v207
	v_med3_i32 v5, v5, s28, v207
	v_med3_i32 v6, v6, s28, v207
	v_med3_i32 v7, v7, s28, v207
	v_med3_i32 v8, v8, s28, v207
	v_med3_i32 v9, v9, s28, v207
	v_med3_i32 v10, v10, s28, v207
	v_med3_i32 v11, v11, s28, v207
	v_med3_i32 v12, v12, s28, v207
	v_med3_i32 v13, v13, s28, v207
	v_med3_i32 v14, v14, s28, v207
	v_med3_i32 v15, v15, s28, v207
	v_med3_i32 v16, v16, s28, v207
	v_med3_i32 v17, v17, s28, v207
	v_med3_i32 v129, v129, s28, v207
	v_add_u32_e32 v131, 36, v2
	v_lshl_add_u32 v139, v134, 2, s26
	v_add_u32_e32 v134, 21, v2
	v_med3_i32 v142, v142, s28, v207
	v_lshl_add_u32 v4, v4, 2, s26
	v_lshl_add_u32 v5, v5, 2, s26
	v_lshl_add_u32 v6, v6, 2, s26
	v_lshl_add_u32 v7, v7, 2, s26
	v_lshl_add_u32 v8, v8, 2, s26
	v_lshl_add_u32 v9, v9, 2, s26
	v_lshl_add_u32 v10, v10, 2, s26
	v_lshl_add_u32 v11, v11, 2, s26
	v_lshl_add_u32 v12, v12, 2, s26
	v_lshl_add_u32 v13, v13, 2, s26
	v_lshl_add_u32 v14, v14, 2, s26
	v_lshl_add_u32 v15, v15, 2, s26
	v_lshl_add_u32 v16, v16, 2, s26
	v_lshl_add_u32 v17, v17, 2, s26
	v_lshl_add_u32 v129, v129, 2, s26
	v_med3_i32 v131, v131, s28, v207
	v_med3_i32 v134, v134, s28, v207
	v_lshl_add_u32 v145, v142, 2, s26
	v_add_u32_e32 v142, 7, v2
	ds_read_b32 v4, v4 offset:512
	ds_read_b32 v5, v5 offset:512
	ds_read_b32 v6, v6 offset:512
	ds_read_b32 v7, v7 offset:512
	ds_read_b32 v8, v8 offset:512
	ds_read_b32 v9, v9 offset:512
	ds_read_b32 v10, v10 offset:512
	ds_read_b32 v11, v11 offset:512
	v_lshl_add_u32 v131, v131, 2, s26
	ds_read_b32 v12, v12 offset:512
	ds_read_b32 v13, v13 offset:512
	ds_read_b32 v14, v14 offset:512
	ds_read_b32 v15, v15 offset:512
	ds_read_b32 v16, v16 offset:512
	ds_read_b32 v17, v17 offset:512
	ds_read_b32 v132, v129 offset:512
	ds_read_b32 v133, v131 offset:512
	v_add_u32_e32 v129, 31, v2
	v_lshl_add_u32 v140, v134, 2, s26
	v_add_u32_e32 v134, 20, v2
	v_med3_i32 v142, v142, s28, v207
	v_med3_i32 v129, v129, s28, v207
	v_add_u32_e32 v131, 30, v2
	v_med3_i32 v134, v134, s28, v207
	v_lshl_add_u32 v146, v142, 2, s26
	v_add_u32_e32 v142, 6, v2
	v_lshl_add_u32 v129, v129, 2, s26
	v_med3_i32 v131, v131, s28, v207
	v_lshl_add_u32 v141, v134, 2, s26
	v_med3_i32 v142, v142, s28, v207
	v_lshl_add_u32 v131, v131, 2, s26
	ds_read_b32 v134, v129 offset:512
	ds_read_b32 v135, v131 offset:512
	ds_read_b32 v136, v136 offset:512
	ds_read_b32 v137, v137 offset:512
	ds_read_b32 v138, v138 offset:512
	ds_read_b32 v139, v139 offset:512
	ds_read_b32 v140, v140 offset:512
	ds_read_b32 v141, v141 offset:512
	v_add_u32_e32 v129, 15, v2
	v_lshl_add_u32 v147, v142, 2, s26
	v_add_u32_e32 v142, 5, v2
	v_med3_i32 v129, v129, s28, v207
	v_add_u32_e32 v131, 14, v2
	v_med3_i32 v142, v142, s28, v207
	v_add_u32_e32 v2, 4, v2
	v_lshl_add_u32 v129, v129, 2, s26
	v_med3_i32 v131, v131, s28, v207
	v_lshl_add_u32 v148, v142, 2, s26
	v_med3_i32 v2, v2, s28, v207
	v_lshl_add_u32 v131, v131, 2, s26
	v_lshl_add_u32 v2, v2, 2, s26
	ds_read_b32 v142, v129 offset:512
	ds_read_b32 v143, v131 offset:512
	ds_read_b32 v144, v144 offset:512
	ds_read_b32 v145, v145 offset:512
	ds_read_b32 v146, v146 offset:512
	ds_read_b32 v147, v147 offset:512
	ds_read_b32 v148, v148 offset:512
	ds_read_b32 v149, v2 offset:512
	s_waitcnt lgkmcnt(14)
	v_pk_add_f32 v[96:97], v[96:97], v[132:133]
	v_pk_add_f32 v[94:95], v[94:95], v[16:17]
	v_pk_add_f32 v[92:93], v[92:93], v[14:15]
	v_pk_add_f32 v[90:91], v[90:91], v[12:13]
	v_pk_add_f32 v[88:89], v[88:89], v[10:11]
	v_pk_add_f32 v[86:87], v[86:87], v[8:9]
	v_pk_add_f32 v[84:85], v[84:85], v[6:7]
	v_pk_add_f32 v[82:83], v[82:83], v[4:5]
	s_waitcnt lgkmcnt(0)
	v_pk_add_f32 v[80:81], v[80:81], v[148:149]
	v_pk_add_f32 v[78:79], v[78:79], v[146:147]
	v_pk_add_f32 v[76:77], v[76:77], v[144:145]
	v_pk_add_f32 v[74:75], v[74:75], v[142:143]
	v_pk_add_f32 v[72:73], v[72:73], v[140:141]
	v_pk_add_f32 v[70:71], v[70:71], v[138:139]
	v_pk_add_f32 v[68:69], v[68:69], v[136:137]
	v_pk_add_f32 v[66:67], v[66:67], v[134:135]
